# P3 epilogue: the merge-gate loads (read exactly once) are non-temporal
# speedup vs baseline: 1.0090x; 1.0090x over previous
.LBB0_340:
	s_lshl_b32 s86, s26, 8
	s_lshl_b32 s87, s28, 3
	s_add_i32 s86, s86, s87
	s_mul_i32 s86, s86, 0xc000
	s_add_u32 s78, s74, s86
	s_addc_u32 s79, s75, 0
	s_add_u32 s78, s78, 0x8000
	s_addc_u32 s79, s79, 0
	s_add_u32 s76, s78, 0x600000
	s_addc_u32 s77, s79, 0
	s_add_u32 s88, s76, 0x2000
	s_addc_u32 s89, s77, 0
	s_add_u32 s90, s78, 0x2000
	s_addc_u32 s91, s79, 0
	s_lshl_b32 s86, s26, 21
	s_lshl_b32 s87, s28, 9
	s_add_u32 s86, s86, s87
	s_add_u32 s72, s4, s86
	s_addc_u32 s73, s5, 0
	v_lshlrev_b32_e32 v142, 4, v183
	v_lshlrev_b32_e32 v143, 13, v162
	v_lshl_add_u32 v143, v164, 1, v143
	s_cmp_eq_u32 s33, 0
	s_cselect_b64 s[0:1], -1, 0
	s_cbranch_scc0 .Lp3e_half1
	global_load_dwordx4 v[166:169], v142, s[76:77] nt
	global_load_dwordx4 v[170:173], v142, s[78:79] nt
	global_load_dwordx4 v[174:177], v142, s[88:89] nt
	global_load_dwordx4 v[178:181], v142, s[90:91] nt
	v_add_u32_e32 v145, 0xc000, v142
	global_load_dwordx4 v[184:187], v145, s[76:77] nt
	global_load_dwordx4 v[188:191], v145, s[78:79] nt
	global_load_dwordx4 v[192:195], v145, s[88:89] nt
	global_load_dwordx4 v[196:199], v145, s[90:91] nt
	v_add_u32_e32 v144, 0x18000, v142
	global_load_dwordx4 v[200:203], v144, s[76:77] nt
	global_load_dwordx4 v[204:207], v144, s[78:79] nt
	global_load_dwordx4 v[208:211], v144, s[88:89] nt
	global_load_dwordx4 v[212:215], v144, s[90:91] nt
	v_add_u32_e32 v145, 0x24000, v142
	global_load_dwordx4 v[216:219], v145, s[76:77] nt
	global_load_dwordx4 v[220:223], v145, s[78:79] nt
	global_load_dwordx4 v[224:227], v145, s[88:89] nt
	global_load_dwordx4 v[228:231], v145, s[90:91] nt
	s_waitcnt vmcnt(14)
	v_lshlrev_b32_e32 v146, 16, v166
	v_and_b32_e32 v147, 0xffff0000, v166
	v_lshlrev_b32_e32 v148, 16, v167
	v_and_b32_e32 v149, 0xffff0000, v167
	v_lshlrev_b32_e32 v150, 16, v168
	v_and_b32_e32 v151, 0xffff0000, v168
	v_lshlrev_b32_e32 v152, 16, v169
	v_and_b32_e32 v153, 0xffff0000, v169
	v_rcp_f32_e32 v146, v146
	v_rcp_f32_e32 v147, v147
	v_rcp_f32_e32 v148, v148
	v_rcp_f32_e32 v149, v149
	v_rcp_f32_e32 v150, v150
	v_rcp_f32_e32 v151, v151
	v_rcp_f32_e32 v152, v152
	v_rcp_f32_e32 v153, v153
	v_lshlrev_b32_e32 v154, 16, v170
	v_and_b32_e32 v155, 0xffff0000, v170
	v_lshlrev_b32_e32 v156, 16, v171
	v_and_b32_e32 v157, 0xffff0000, v171
	v_lshlrev_b32_e32 v158, 16, v172
	v_and_b32_e32 v159, 0xffff0000, v172
	v_lshlrev_b32_e32 v160, 16, v173
	v_and_b32_e32 v161, 0xffff0000, v173
	v_pk_mul_f32 v[146:147], v[146:147], v[154:155]
	v_pk_mul_f32 v[148:149], v[148:149], v[156:157]
	v_pk_mul_f32 v[150:151], v[150:151], v[158:159]
	v_pk_mul_f32 v[152:153], v[152:153], v[160:161]
	v_pk_mul_f32 v[124:125], v[124:125], v[146:147]
	v_pk_mul_f32 v[126:127], v[126:127], v[148:149]
	v_pk_mul_f32 v[120:121], v[120:121], v[150:151]
	v_pk_mul_f32 v[122:123], v[122:123], v[152:153]
	s_waitcnt vmcnt(12)
	v_lshlrev_b32_e32 v146, 16, v174
	v_and_b32_e32 v147, 0xffff0000, v174
	v_lshlrev_b32_e32 v148, 16, v175
	v_and_b32_e32 v149, 0xffff0000, v175
	v_lshlrev_b32_e32 v150, 16, v176
	v_and_b32_e32 v151, 0xffff0000, v176
	v_lshlrev_b32_e32 v152, 16, v177
	v_and_b32_e32 v153, 0xffff0000, v177
	v_rcp_f32_e32 v146, v146
	v_rcp_f32_e32 v147, v147
	v_rcp_f32_e32 v148, v148
	v_rcp_f32_e32 v149, v149
	v_rcp_f32_e32 v150, v150
	v_rcp_f32_e32 v151, v151
	v_rcp_f32_e32 v152, v152
	v_rcp_f32_e32 v153, v153
	v_lshlrev_b32_e32 v154, 16, v178
	v_and_b32_e32 v155, 0xffff0000, v178
	v_lshlrev_b32_e32 v156, 16, v179
	v_and_b32_e32 v157, 0xffff0000, v179
	v_lshlrev_b32_e32 v158, 16, v180
	v_and_b32_e32 v159, 0xffff0000, v180
	v_lshlrev_b32_e32 v160, 16, v181
	v_and_b32_e32 v161, 0xffff0000, v181
	v_pk_mul_f32 v[146:147], v[146:147], v[154:155]
	v_pk_mul_f32 v[148:149], v[148:149], v[156:157]
	v_pk_mul_f32 v[150:151], v[150:151], v[158:159]
	v_pk_mul_f32 v[152:153], v[152:153], v[160:161]
	v_pk_mul_f32 v[92:93], v[92:93], v[146:147]
	v_pk_mul_f32 v[94:95], v[94:95], v[148:149]
	v_pk_mul_f32 v[88:89], v[88:89], v[150:151]
	v_pk_mul_f32 v[90:91], v[90:91], v[152:153]
	s_waitcnt vmcnt(10)
	v_lshlrev_b32_e32 v146, 16, v184
	v_and_b32_e32 v147, 0xffff0000, v184
	v_lshlrev_b32_e32 v148, 16, v185
	v_and_b32_e32 v149, 0xffff0000, v185
	v_lshlrev_b32_e32 v150, 16, v186
	v_and_b32_e32 v151, 0xffff0000, v186
	v_lshlrev_b32_e32 v152, 16, v187
	v_and_b32_e32 v153, 0xffff0000, v187
	v_rcp_f32_e32 v146, v146
	v_rcp_f32_e32 v147, v147
	v_rcp_f32_e32 v148, v148
	v_rcp_f32_e32 v149, v149
	v_rcp_f32_e32 v150, v150
	v_rcp_f32_e32 v151, v151
	v_rcp_f32_e32 v152, v152
	v_rcp_f32_e32 v153, v153
	v_lshlrev_b32_e32 v154, 16, v188
	v_and_b32_e32 v155, 0xffff0000, v188
	v_lshlrev_b32_e32 v156, 16, v189
	v_and_b32_e32 v157, 0xffff0000, v189
	v_lshlrev_b32_e32 v158, 16, v190
	v_and_b32_e32 v159, 0xffff0000, v190
	v_lshlrev_b32_e32 v160, 16, v191
	v_and_b32_e32 v161, 0xffff0000, v191
	v_pk_mul_f32 v[146:147], v[146:147], v[154:155]
	v_pk_mul_f32 v[148:149], v[148:149], v[156:157]
	v_pk_mul_f32 v[150:151], v[150:151], v[158:159]
	v_pk_mul_f32 v[152:153], v[152:153], v[160:161]
	v_pk_mul_f32 v[116:117], v[116:117], v[146:147]
	v_pk_mul_f32 v[118:119], v[118:119], v[148:149]
	v_pk_mul_f32 v[112:113], v[112:113], v[150:151]
	v_pk_mul_f32 v[114:115], v[114:115], v[152:153]
	s_waitcnt vmcnt(8)
	v_lshlrev_b32_e32 v146, 16, v192
	v_and_b32_e32 v147, 0xffff0000, v192
	v_lshlrev_b32_e32 v148, 16, v193
	v_and_b32_e32 v149, 0xffff0000, v193
	v_lshlrev_b32_e32 v150, 16, v194
	v_and_b32_e32 v151, 0xffff0000, v194
	v_lshlrev_b32_e32 v152, 16, v195
	v_and_b32_e32 v153, 0xffff0000, v195
	v_rcp_f32_e32 v146, v146
	v_rcp_f32_e32 v147, v147
	v_rcp_f32_e32 v148, v148
	v_rcp_f32_e32 v149, v149
	v_rcp_f32_e32 v150, v150
	v_rcp_f32_e32 v151, v151
	v_rcp_f32_e32 v152, v152
	v_rcp_f32_e32 v153, v153
	v_lshlrev_b32_e32 v154, 16, v196
	v_and_b32_e32 v155, 0xffff0000, v196
	v_lshlrev_b32_e32 v156, 16, v197
	v_and_b32_e32 v157, 0xffff0000, v197
	v_lshlrev_b32_e32 v158, 16, v198
	v_and_b32_e32 v159, 0xffff0000, v198
	v_lshlrev_b32_e32 v160, 16, v199
	v_and_b32_e32 v161, 0xffff0000, v199
	v_pk_mul_f32 v[146:147], v[146:147], v[154:155]
	v_pk_mul_f32 v[148:149], v[148:149], v[156:157]
	v_pk_mul_f32 v[150:151], v[150:151], v[158:159]
	v_pk_mul_f32 v[152:153], v[152:153], v[160:161]
	v_pk_mul_f32 v[84:85], v[84:85], v[146:147]
	v_pk_mul_f32 v[86:87], v[86:87], v[148:149]
	v_pk_mul_f32 v[80:81], v[80:81], v[150:151]
	v_pk_mul_f32 v[82:83], v[82:83], v[152:153]
	v_add_u32_e32 v144, 0x30000, v142
	global_load_dwordx4 v[166:169], v144, s[76:77] nt
	global_load_dwordx4 v[170:173], v144, s[78:79] nt
	global_load_dwordx4 v[174:177], v144, s[88:89] nt
	global_load_dwordx4 v[178:181], v144, s[90:91] nt
	v_add_u32_e32 v145, 0x3c000, v142
	global_load_dwordx4 v[184:187], v145, s[76:77] nt
	global_load_dwordx4 v[188:191], v145, s[78:79] nt
	global_load_dwordx4 v[192:195], v145, s[88:89] nt
	global_load_dwordx4 v[196:199], v145, s[90:91] nt
	s_waitcnt vmcnt(14)
	v_lshlrev_b32_e32 v146, 16, v200
	v_and_b32_e32 v147, 0xffff0000, v200
	v_lshlrev_b32_e32 v148, 16, v201
	v_and_b32_e32 v149, 0xffff0000, v201
	v_lshlrev_b32_e32 v150, 16, v202
	v_and_b32_e32 v151, 0xffff0000, v202
	v_lshlrev_b32_e32 v152, 16, v203
	v_and_b32_e32 v153, 0xffff0000, v203
	v_rcp_f32_e32 v146, v146
	v_rcp_f32_e32 v147, v147
	v_rcp_f32_e32 v148, v148
	v_rcp_f32_e32 v149, v149
	v_rcp_f32_e32 v150, v150
	v_rcp_f32_e32 v151, v151
	v_rcp_f32_e32 v152, v152
	v_rcp_f32_e32 v153, v153
	v_lshlrev_b32_e32 v154, 16, v204
	v_and_b32_e32 v155, 0xffff0000, v204
	v_lshlrev_b32_e32 v156, 16, v205
	v_and_b32_e32 v157, 0xffff0000, v205
	v_lshlrev_b32_e32 v158, 16, v206
	v_and_b32_e32 v159, 0xffff0000, v206
	v_lshlrev_b32_e32 v160, 16, v207
	v_and_b32_e32 v161, 0xffff0000, v207
	v_pk_mul_f32 v[146:147], v[146:147], v[154:155]
	v_pk_mul_f32 v[148:149], v[148:149], v[156:157]
	v_pk_mul_f32 v[150:151], v[150:151], v[158:159]
	v_pk_mul_f32 v[152:153], v[152:153], v[160:161]
	v_pk_mul_f32 v[108:109], v[108:109], v[146:147]
	v_pk_mul_f32 v[110:111], v[110:111], v[148:149]
	v_pk_mul_f32 v[104:105], v[104:105], v[150:151]
	v_pk_mul_f32 v[106:107], v[106:107], v[152:153]
	s_waitcnt vmcnt(12)
	v_lshlrev_b32_e32 v146, 16, v208
	v_and_b32_e32 v147, 0xffff0000, v208
	v_lshlrev_b32_e32 v148, 16, v209
	v_and_b32_e32 v149, 0xffff0000, v209
	v_lshlrev_b32_e32 v150, 16, v210
	v_and_b32_e32 v151, 0xffff0000, v210
	v_lshlrev_b32_e32 v152, 16, v211
	v_and_b32_e32 v153, 0xffff0000, v211
	v_rcp_f32_e32 v146, v146
	v_rcp_f32_e32 v147, v147
	v_rcp_f32_e32 v148, v148
	v_rcp_f32_e32 v149, v149
	v_rcp_f32_e32 v150, v150
	v_rcp_f32_e32 v151, v151
	v_rcp_f32_e32 v152, v152
	v_rcp_f32_e32 v153, v153
	v_lshlrev_b32_e32 v154, 16, v212
	v_and_b32_e32 v155, 0xffff0000, v212
	v_lshlrev_b32_e32 v156, 16, v213
	v_and_b32_e32 v157, 0xffff0000, v213
	v_lshlrev_b32_e32 v158, 16, v214
	v_and_b32_e32 v159, 0xffff0000, v214
	v_lshlrev_b32_e32 v160, 16, v215
	v_and_b32_e32 v161, 0xffff0000, v215
	v_pk_mul_f32 v[146:147], v[146:147], v[154:155]
	v_pk_mul_f32 v[148:149], v[148:149], v[156:157]
	v_pk_mul_f32 v[150:151], v[150:151], v[158:159]
	v_pk_mul_f32 v[152:153], v[152:153], v[160:161]
	v_pk_mul_f32 v[76:77], v[76:77], v[146:147]
	v_pk_mul_f32 v[78:79], v[78:79], v[148:149]
	v_pk_mul_f32 v[72:73], v[72:73], v[150:151]
	v_pk_mul_f32 v[74:75], v[74:75], v[152:153]
	s_waitcnt vmcnt(10)
	v_lshlrev_b32_e32 v146, 16, v216
	v_and_b32_e32 v147, 0xffff0000, v216
	v_lshlrev_b32_e32 v148, 16, v217
	v_and_b32_e32 v149, 0xffff0000, v217
	v_lshlrev_b32_e32 v150, 16, v218
	v_and_b32_e32 v151, 0xffff0000, v218
	v_lshlrev_b32_e32 v152, 16, v219
	v_and_b32_e32 v153, 0xffff0000, v219
	v_rcp_f32_e32 v146, v146
	v_rcp_f32_e32 v147, v147
	v_rcp_f32_e32 v148, v148
	v_rcp_f32_e32 v149, v149
	v_rcp_f32_e32 v150, v150
	v_rcp_f32_e32 v151, v151
	v_rcp_f32_e32 v152, v152
	v_rcp_f32_e32 v153, v153
	v_lshlrev_b32_e32 v154, 16, v220
	v_and_b32_e32 v155, 0xffff0000, v220
	v_lshlrev_b32_e32 v156, 16, v221
	v_and_b32_e32 v157, 0xffff0000, v221
	v_lshlrev_b32_e32 v158, 16, v222
	v_and_b32_e32 v159, 0xffff0000, v222
	v_lshlrev_b32_e32 v160, 16, v223
	v_and_b32_e32 v161, 0xffff0000, v223
	v_pk_mul_f32 v[146:147], v[146:147], v[154:155]
	v_pk_mul_f32 v[148:149], v[148:149], v[156:157]
	v_pk_mul_f32 v[150:151], v[150:151], v[158:159]
	v_pk_mul_f32 v[152:153], v[152:153], v[160:161]
	v_pk_mul_f32 v[100:101], v[100:101], v[146:147]
	v_pk_mul_f32 v[102:103], v[102:103], v[148:149]
	v_pk_mul_f32 v[96:97], v[96:97], v[150:151]
	v_pk_mul_f32 v[98:99], v[98:99], v[152:153]
	s_waitcnt vmcnt(8)
	v_lshlrev_b32_e32 v146, 16, v224
	v_and_b32_e32 v147, 0xffff0000, v224
	v_lshlrev_b32_e32 v148, 16, v225
	v_and_b32_e32 v149, 0xffff0000, v225
	v_lshlrev_b32_e32 v150, 16, v226
	v_and_b32_e32 v151, 0xffff0000, v226
	v_lshlrev_b32_e32 v152, 16, v227
	v_and_b32_e32 v153, 0xffff0000, v227
	v_rcp_f32_e32 v146, v146
	v_rcp_f32_e32 v147, v147
	v_rcp_f32_e32 v148, v148
	v_rcp_f32_e32 v149, v149
	v_rcp_f32_e32 v150, v150
	v_rcp_f32_e32 v151, v151
	v_rcp_f32_e32 v152, v152
	v_rcp_f32_e32 v153, v153
	v_lshlrev_b32_e32 v154, 16, v228
	v_and_b32_e32 v155, 0xffff0000, v228
	v_lshlrev_b32_e32 v156, 16, v229
	v_and_b32_e32 v157, 0xffff0000, v229
	v_lshlrev_b32_e32 v158, 16, v230
	v_and_b32_e32 v159, 0xffff0000, v230
	v_lshlrev_b32_e32 v160, 16, v231
	v_and_b32_e32 v161, 0xffff0000, v231
	v_pk_mul_f32 v[146:147], v[146:147], v[154:155]
	v_pk_mul_f32 v[148:149], v[148:149], v[156:157]
	v_pk_mul_f32 v[150:151], v[150:151], v[158:159]
	v_pk_mul_f32 v[152:153], v[152:153], v[160:161]
	v_pk_mul_f32 v[68:69], v[68:69], v[146:147]
	v_pk_mul_f32 v[70:71], v[70:71], v[148:149]
	v_pk_mul_f32 v[64:65], v[64:65], v[150:151]
	v_pk_mul_f32 v[66:67], v[66:67], v[152:153]
	v_add_u32_e32 v144, 0x48000, v142
	global_load_dwordx4 v[200:203], v144, s[76:77] nt
	global_load_dwordx4 v[204:207], v144, s[78:79] nt
	global_load_dwordx4 v[208:211], v144, s[88:89] nt
	global_load_dwordx4 v[212:215], v144, s[90:91] nt
	v_add_u32_e32 v145, 0x54000, v142
	global_load_dwordx4 v[216:219], v145, s[76:77] nt
	global_load_dwordx4 v[220:223], v145, s[78:79] nt
	global_load_dwordx4 v[224:227], v145, s[88:89] nt
	global_load_dwordx4 v[228:231], v145, s[90:91] nt
	s_waitcnt vmcnt(14)
	v_lshlrev_b32_e32 v146, 16, v166
	v_and_b32_e32 v147, 0xffff0000, v166
	v_lshlrev_b32_e32 v148, 16, v167
	v_and_b32_e32 v149, 0xffff0000, v167
	v_lshlrev_b32_e32 v150, 16, v168
	v_and_b32_e32 v151, 0xffff0000, v168
	v_lshlrev_b32_e32 v152, 16, v169
	v_and_b32_e32 v153, 0xffff0000, v169
	v_rcp_f32_e32 v146, v146
	v_rcp_f32_e32 v147, v147
	v_rcp_f32_e32 v148, v148
	v_rcp_f32_e32 v149, v149
	v_rcp_f32_e32 v150, v150
	v_rcp_f32_e32 v151, v151
	v_rcp_f32_e32 v152, v152
	v_rcp_f32_e32 v153, v153
	v_lshlrev_b32_e32 v154, 16, v170
	v_and_b32_e32 v155, 0xffff0000, v170
	v_lshlrev_b32_e32 v156, 16, v171
	v_and_b32_e32 v157, 0xffff0000, v171
	v_lshlrev_b32_e32 v158, 16, v172
	v_and_b32_e32 v159, 0xffff0000, v172
	v_lshlrev_b32_e32 v160, 16, v173
	v_and_b32_e32 v161, 0xffff0000, v173
	v_pk_mul_f32 v[146:147], v[146:147], v[154:155]
	v_pk_mul_f32 v[148:149], v[148:149], v[156:157]
	v_pk_mul_f32 v[150:151], v[150:151], v[158:159]
	v_pk_mul_f32 v[152:153], v[152:153], v[160:161]
	v_pk_mul_f32 v[60:61], v[60:61], v[146:147]
	v_pk_mul_f32 v[62:63], v[62:63], v[148:149]
	v_pk_mul_f32 v[56:57], v[56:57], v[150:151]
	v_pk_mul_f32 v[58:59], v[58:59], v[152:153]
	s_waitcnt vmcnt(12)
	v_lshlrev_b32_e32 v146, 16, v174
	v_and_b32_e32 v147, 0xffff0000, v174
	v_lshlrev_b32_e32 v148, 16, v175
	v_and_b32_e32 v149, 0xffff0000, v175
	v_lshlrev_b32_e32 v150, 16, v176
	v_and_b32_e32 v151, 0xffff0000, v176
	v_lshlrev_b32_e32 v152, 16, v177
	v_and_b32_e32 v153, 0xffff0000, v177
	v_rcp_f32_e32 v146, v146
	v_rcp_f32_e32 v147, v147
	v_rcp_f32_e32 v148, v148
	v_rcp_f32_e32 v149, v149
	v_rcp_f32_e32 v150, v150
	v_rcp_f32_e32 v151, v151
	v_rcp_f32_e32 v152, v152
	v_rcp_f32_e32 v153, v153
	v_lshlrev_b32_e32 v154, 16, v178
	v_and_b32_e32 v155, 0xffff0000, v178
	v_lshlrev_b32_e32 v156, 16, v179
	v_and_b32_e32 v157, 0xffff0000, v179
	v_lshlrev_b32_e32 v158, 16, v180
	v_and_b32_e32 v159, 0xffff0000, v180
	v_lshlrev_b32_e32 v160, 16, v181
	v_and_b32_e32 v161, 0xffff0000, v181
	v_pk_mul_f32 v[146:147], v[146:147], v[154:155]
	v_pk_mul_f32 v[148:149], v[148:149], v[156:157]
	v_pk_mul_f32 v[150:151], v[150:151], v[158:159]
	v_pk_mul_f32 v[152:153], v[152:153], v[160:161]
	v_pk_mul_f32 v[28:29], v[28:29], v[146:147]
	v_pk_mul_f32 v[30:31], v[30:31], v[148:149]
	v_pk_mul_f32 v[24:25], v[24:25], v[150:151]
	v_pk_mul_f32 v[26:27], v[26:27], v[152:153]
	s_waitcnt vmcnt(10)
	v_lshlrev_b32_e32 v146, 16, v184
	v_and_b32_e32 v147, 0xffff0000, v184
	v_lshlrev_b32_e32 v148, 16, v185
	v_and_b32_e32 v149, 0xffff0000, v185
	v_lshlrev_b32_e32 v150, 16, v186
	v_and_b32_e32 v151, 0xffff0000, v186
	v_lshlrev_b32_e32 v152, 16, v187
	v_and_b32_e32 v153, 0xffff0000, v187
	v_rcp_f32_e32 v146, v146
	v_rcp_f32_e32 v147, v147
	v_rcp_f32_e32 v148, v148
	v_rcp_f32_e32 v149, v149
	v_rcp_f32_e32 v150, v150
	v_rcp_f32_e32 v151, v151
	v_rcp_f32_e32 v152, v152
	v_rcp_f32_e32 v153, v153
	v_lshlrev_b32_e32 v154, 16, v188
	v_and_b32_e32 v155, 0xffff0000, v188
	v_lshlrev_b32_e32 v156, 16, v189
	v_and_b32_e32 v157, 0xffff0000, v189
	v_lshlrev_b32_e32 v158, 16, v190
	v_and_b32_e32 v159, 0xffff0000, v190
	v_lshlrev_b32_e32 v160, 16, v191
	v_and_b32_e32 v161, 0xffff0000, v191
	v_pk_mul_f32 v[146:147], v[146:147], v[154:155]
	v_pk_mul_f32 v[148:149], v[148:149], v[156:157]
	v_pk_mul_f32 v[150:151], v[150:151], v[158:159]
	v_pk_mul_f32 v[152:153], v[152:153], v[160:161]
	v_pk_mul_f32 v[52:53], v[52:53], v[146:147]
	v_pk_mul_f32 v[54:55], v[54:55], v[148:149]
	v_pk_mul_f32 v[48:49], v[48:49], v[150:151]
	v_pk_mul_f32 v[50:51], v[50:51], v[152:153]
	s_waitcnt vmcnt(8)
	v_lshlrev_b32_e32 v146, 16, v192
	v_and_b32_e32 v147, 0xffff0000, v192
	v_lshlrev_b32_e32 v148, 16, v193
	v_and_b32_e32 v149, 0xffff0000, v193
	v_lshlrev_b32_e32 v150, 16, v194
	v_and_b32_e32 v151, 0xffff0000, v194
	v_lshlrev_b32_e32 v152, 16, v195
	v_and_b32_e32 v153, 0xffff0000, v195
	v_rcp_f32_e32 v146, v146
	v_rcp_f32_e32 v147, v147
	v_rcp_f32_e32 v148, v148
	v_rcp_f32_e32 v149, v149
	v_rcp_f32_e32 v150, v150
	v_rcp_f32_e32 v151, v151
	v_rcp_f32_e32 v152, v152
	v_rcp_f32_e32 v153, v153
	v_lshlrev_b32_e32 v154, 16, v196
	v_and_b32_e32 v155, 0xffff0000, v196
	v_lshlrev_b32_e32 v156, 16, v197
	v_and_b32_e32 v157, 0xffff0000, v197
	v_lshlrev_b32_e32 v158, 16, v198
	v_and_b32_e32 v159, 0xffff0000, v198
	v_lshlrev_b32_e32 v160, 16, v199
	v_and_b32_e32 v161, 0xffff0000, v199
	v_pk_mul_f32 v[146:147], v[146:147], v[154:155]
	v_pk_mul_f32 v[148:149], v[148:149], v[156:157]
	v_pk_mul_f32 v[150:151], v[150:151], v[158:159]
	v_pk_mul_f32 v[152:153], v[152:153], v[160:161]
	v_pk_mul_f32 v[20:21], v[20:21], v[146:147]
	v_pk_mul_f32 v[22:23], v[22:23], v[148:149]
	v_pk_mul_f32 v[16:17], v[16:17], v[150:151]
	v_pk_mul_f32 v[18:19], v[18:19], v[152:153]
	s_waitcnt vmcnt(6)
	v_lshlrev_b32_e32 v146, 16, v200
	v_and_b32_e32 v147, 0xffff0000, v200
	v_lshlrev_b32_e32 v148, 16, v201
	v_and_b32_e32 v149, 0xffff0000, v201
	v_lshlrev_b32_e32 v150, 16, v202
	v_and_b32_e32 v151, 0xffff0000, v202
	v_lshlrev_b32_e32 v152, 16, v203
	v_and_b32_e32 v153, 0xffff0000, v203
	v_rcp_f32_e32 v146, v146
	v_rcp_f32_e32 v147, v147
	v_rcp_f32_e32 v148, v148
	v_rcp_f32_e32 v149, v149
	v_rcp_f32_e32 v150, v150
	v_rcp_f32_e32 v151, v151
	v_rcp_f32_e32 v152, v152
	v_rcp_f32_e32 v153, v153
	v_lshlrev_b32_e32 v154, 16, v204
	v_and_b32_e32 v155, 0xffff0000, v204
	v_lshlrev_b32_e32 v156, 16, v205
	v_and_b32_e32 v157, 0xffff0000, v205
	v_lshlrev_b32_e32 v158, 16, v206
	v_and_b32_e32 v159, 0xffff0000, v206
	v_lshlrev_b32_e32 v160, 16, v207
	v_and_b32_e32 v161, 0xffff0000, v207
	v_pk_mul_f32 v[146:147], v[146:147], v[154:155]
	v_pk_mul_f32 v[148:149], v[148:149], v[156:157]
	v_pk_mul_f32 v[150:151], v[150:151], v[158:159]
	v_pk_mul_f32 v[152:153], v[152:153], v[160:161]
	v_pk_mul_f32 v[44:45], v[44:45], v[146:147]
	v_pk_mul_f32 v[46:47], v[46:47], v[148:149]
	v_pk_mul_f32 v[40:41], v[40:41], v[150:151]
	v_pk_mul_f32 v[42:43], v[42:43], v[152:153]
	s_waitcnt vmcnt(4)
	v_lshlrev_b32_e32 v146, 16, v208
	v_and_b32_e32 v147, 0xffff0000, v208
	v_lshlrev_b32_e32 v148, 16, v209
	v_and_b32_e32 v149, 0xffff0000, v209
	v_lshlrev_b32_e32 v150, 16, v210
	v_and_b32_e32 v151, 0xffff0000, v210
	v_lshlrev_b32_e32 v152, 16, v211
	v_and_b32_e32 v153, 0xffff0000, v211
	v_rcp_f32_e32 v146, v146
	v_rcp_f32_e32 v147, v147
	v_rcp_f32_e32 v148, v148
	v_rcp_f32_e32 v149, v149
	v_rcp_f32_e32 v150, v150
	v_rcp_f32_e32 v151, v151
	v_rcp_f32_e32 v152, v152
	v_rcp_f32_e32 v153, v153
	v_lshlrev_b32_e32 v154, 16, v212
	v_and_b32_e32 v155, 0xffff0000, v212
	v_lshlrev_b32_e32 v156, 16, v213
	v_and_b32_e32 v157, 0xffff0000, v213
	v_lshlrev_b32_e32 v158, 16, v214
	v_and_b32_e32 v159, 0xffff0000, v214
	v_lshlrev_b32_e32 v160, 16, v215
	v_and_b32_e32 v161, 0xffff0000, v215
	v_pk_mul_f32 v[146:147], v[146:147], v[154:155]
	v_pk_mul_f32 v[148:149], v[148:149], v[156:157]
	v_pk_mul_f32 v[150:151], v[150:151], v[158:159]
	v_pk_mul_f32 v[152:153], v[152:153], v[160:161]
	v_pk_mul_f32 v[12:13], v[12:13], v[146:147]
	v_pk_mul_f32 v[14:15], v[14:15], v[148:149]
	v_pk_mul_f32 v[8:9], v[8:9], v[150:151]
	v_pk_mul_f32 v[10:11], v[10:11], v[152:153]
	s_waitcnt vmcnt(2)
	v_lshlrev_b32_e32 v146, 16, v216
	v_and_b32_e32 v147, 0xffff0000, v216
	v_lshlrev_b32_e32 v148, 16, v217
	v_and_b32_e32 v149, 0xffff0000, v217
	v_lshlrev_b32_e32 v150, 16, v218
	v_and_b32_e32 v151, 0xffff0000, v218
	v_lshlrev_b32_e32 v152, 16, v219
	v_and_b32_e32 v153, 0xffff0000, v219
	v_rcp_f32_e32 v146, v146
	v_rcp_f32_e32 v147, v147
	v_rcp_f32_e32 v148, v148
	v_rcp_f32_e32 v149, v149
	v_rcp_f32_e32 v150, v150
	v_rcp_f32_e32 v151, v151
	v_rcp_f32_e32 v152, v152
	v_rcp_f32_e32 v153, v153
	v_lshlrev_b32_e32 v154, 16, v220
	v_and_b32_e32 v155, 0xffff0000, v220
	v_lshlrev_b32_e32 v156, 16, v221
	v_and_b32_e32 v157, 0xffff0000, v221
	v_lshlrev_b32_e32 v158, 16, v222
	v_and_b32_e32 v159, 0xffff0000, v222
	v_lshlrev_b32_e32 v160, 16, v223
	v_and_b32_e32 v161, 0xffff0000, v223
	v_pk_mul_f32 v[146:147], v[146:147], v[154:155]
	v_pk_mul_f32 v[148:149], v[148:149], v[156:157]
	v_pk_mul_f32 v[150:151], v[150:151], v[158:159]
	v_pk_mul_f32 v[152:153], v[152:153], v[160:161]
	v_pk_mul_f32 v[36:37], v[36:37], v[146:147]
	v_pk_mul_f32 v[38:39], v[38:39], v[148:149]
	v_pk_mul_f32 v[32:33], v[32:33], v[150:151]
	v_pk_mul_f32 v[34:35], v[34:35], v[152:153]
	s_waitcnt vmcnt(0)
	v_lshlrev_b32_e32 v146, 16, v224
	v_and_b32_e32 v147, 0xffff0000, v224
	v_lshlrev_b32_e32 v148, 16, v225
	v_and_b32_e32 v149, 0xffff0000, v225
	v_lshlrev_b32_e32 v150, 16, v226
	v_and_b32_e32 v151, 0xffff0000, v226
	v_lshlrev_b32_e32 v152, 16, v227
	v_and_b32_e32 v153, 0xffff0000, v227
	v_rcp_f32_e32 v146, v146
	v_rcp_f32_e32 v147, v147
	v_rcp_f32_e32 v148, v148
	v_rcp_f32_e32 v149, v149
	v_rcp_f32_e32 v150, v150
	v_rcp_f32_e32 v151, v151
	v_rcp_f32_e32 v152, v152
	v_rcp_f32_e32 v153, v153
	v_lshlrev_b32_e32 v154, 16, v228
	v_and_b32_e32 v155, 0xffff0000, v228
	v_lshlrev_b32_e32 v156, 16, v229
	v_and_b32_e32 v157, 0xffff0000, v229
	v_lshlrev_b32_e32 v158, 16, v230
	v_and_b32_e32 v159, 0xffff0000, v230
	v_lshlrev_b32_e32 v160, 16, v231
	v_and_b32_e32 v161, 0xffff0000, v231
	v_pk_mul_f32 v[146:147], v[146:147], v[154:155]
	v_pk_mul_f32 v[148:149], v[148:149], v[156:157]
	v_pk_mul_f32 v[150:151], v[150:151], v[158:159]
	v_pk_mul_f32 v[152:153], v[152:153], v[160:161]
	v_pk_mul_f32 v[4:5], v[4:5], v[146:147]
	v_pk_mul_f32 v[6:7], v[6:7], v[148:149]
	v_pk_mul_f32 v[0:1], v[0:1], v[150:151]
	v_pk_mul_f32 v[2:3], v[2:3], v[152:153]
	s_branch .Lp3e_done
.Lp3e_half1:
	global_load_dwordx4 v[166:169], v142, s[76:77] nt
	global_load_dwordx4 v[170:173], v142, s[88:89] nt
	v_add_u32_e32 v145, 0xc000, v142
	global_load_dwordx4 v[174:177], v145, s[76:77] nt
	global_load_dwordx4 v[178:181], v145, s[88:89] nt
	v_add_u32_e32 v144, 0x18000, v142
	global_load_dwordx4 v[184:187], v144, s[76:77] nt
	global_load_dwordx4 v[188:191], v144, s[88:89] nt
	v_add_u32_e32 v145, 0x24000, v142
	global_load_dwordx4 v[192:195], v145, s[76:77] nt
	global_load_dwordx4 v[196:199], v145, s[88:89] nt
	v_add_u32_e32 v144, 0x30000, v142
	global_load_dwordx4 v[200:203], v144, s[76:77] nt
	global_load_dwordx4 v[204:207], v144, s[88:89] nt
	v_add_u32_e32 v145, 0x3c000, v142
	global_load_dwordx4 v[208:211], v145, s[76:77] nt
	global_load_dwordx4 v[212:215], v145, s[88:89] nt
	v_add_u32_e32 v144, 0x48000, v142
	global_load_dwordx4 v[216:219], v144, s[76:77] nt
	global_load_dwordx4 v[220:223], v144, s[88:89] nt
	v_add_u32_e32 v145, 0x54000, v142
	global_load_dwordx4 v[224:227], v145, s[76:77] nt
	global_load_dwordx4 v[228:231], v145, s[88:89] nt
	s_waitcnt vmcnt(15)
	v_lshlrev_b32_e32 v146, 16, v166
	v_and_b32_e32 v147, 0xffff0000, v166
	v_lshlrev_b32_e32 v148, 16, v167
	v_and_b32_e32 v149, 0xffff0000, v167
	v_lshlrev_b32_e32 v150, 16, v168
	v_and_b32_e32 v151, 0xffff0000, v168
	v_lshlrev_b32_e32 v152, 16, v169
	v_and_b32_e32 v153, 0xffff0000, v169
	v_pk_mul_f32 v[154:155], v[124:125], v[146:147]
	v_pk_mul_f32 v[156:157], v[126:127], v[148:149]
	v_pk_mul_f32 v[158:159], v[120:121], v[150:151]
	v_pk_mul_f32 v[160:161], v[122:123], v[152:153]
	v_cvt_pk_bf16_f32 v166, v154, v155
	v_cvt_pk_bf16_f32 v167, v156, v157
	v_cvt_pk_bf16_f32 v168, v158, v159
	v_cvt_pk_bf16_f32 v169, v160, v161
	global_store_dwordx4 v143, v[166:169], s[72:73]
	s_waitcnt vmcnt(15)
	v_lshlrev_b32_e32 v146, 16, v170
	v_and_b32_e32 v147, 0xffff0000, v170
	v_lshlrev_b32_e32 v148, 16, v171
	v_and_b32_e32 v149, 0xffff0000, v171
	v_lshlrev_b32_e32 v150, 16, v172
	v_and_b32_e32 v151, 0xffff0000, v172
	v_lshlrev_b32_e32 v152, 16, v173
	v_and_b32_e32 v153, 0xffff0000, v173
	v_pk_mul_f32 v[154:155], v[92:93], v[146:147]
	v_pk_mul_f32 v[156:157], v[94:95], v[148:149]
	v_pk_mul_f32 v[158:159], v[88:89], v[150:151]
	v_pk_mul_f32 v[160:161], v[90:91], v[152:153]
	v_cvt_pk_bf16_f32 v170, v154, v155
	v_cvt_pk_bf16_f32 v171, v156, v157
	v_cvt_pk_bf16_f32 v172, v158, v159
	v_cvt_pk_bf16_f32 v173, v160, v161
	global_store_dwordx4 v143, v[170:173], s[72:73] offset:256
	s_waitcnt vmcnt(15)
	v_lshlrev_b32_e32 v146, 16, v174
	v_and_b32_e32 v147, 0xffff0000, v174
	v_lshlrev_b32_e32 v148, 16, v175
	v_and_b32_e32 v149, 0xffff0000, v175
	v_lshlrev_b32_e32 v150, 16, v176
	v_and_b32_e32 v151, 0xffff0000, v176
	v_lshlrev_b32_e32 v152, 16, v177
	v_and_b32_e32 v153, 0xffff0000, v177
	v_pk_mul_f32 v[154:155], v[116:117], v[146:147]
	v_pk_mul_f32 v[156:157], v[118:119], v[148:149]
	v_pk_mul_f32 v[158:159], v[112:113], v[150:151]
	v_pk_mul_f32 v[160:161], v[114:115], v[152:153]
	v_add_u32_e32 v145, 0x20000, v143
	v_cvt_pk_bf16_f32 v174, v154, v155
	v_cvt_pk_bf16_f32 v175, v156, v157
	v_cvt_pk_bf16_f32 v176, v158, v159
	v_cvt_pk_bf16_f32 v177, v160, v161
	global_store_dwordx4 v145, v[174:177], s[72:73]
	s_waitcnt vmcnt(15)
	v_lshlrev_b32_e32 v146, 16, v178
	v_and_b32_e32 v147, 0xffff0000, v178
	v_lshlrev_b32_e32 v148, 16, v179
	v_and_b32_e32 v149, 0xffff0000, v179
	v_lshlrev_b32_e32 v150, 16, v180
	v_and_b32_e32 v151, 0xffff0000, v180
	v_lshlrev_b32_e32 v152, 16, v181
	v_and_b32_e32 v153, 0xffff0000, v181
	v_pk_mul_f32 v[154:155], v[84:85], v[146:147]
	v_pk_mul_f32 v[156:157], v[86:87], v[148:149]
	v_pk_mul_f32 v[158:159], v[80:81], v[150:151]
	v_pk_mul_f32 v[160:161], v[82:83], v[152:153]
	v_cvt_pk_bf16_f32 v178, v154, v155
	v_cvt_pk_bf16_f32 v179, v156, v157
	v_cvt_pk_bf16_f32 v180, v158, v159
	v_cvt_pk_bf16_f32 v181, v160, v161
	global_store_dwordx4 v145, v[178:181], s[72:73] offset:256
	s_waitcnt vmcnt(15)
	v_lshlrev_b32_e32 v146, 16, v184
	v_and_b32_e32 v147, 0xffff0000, v184
	v_lshlrev_b32_e32 v148, 16, v185
	v_and_b32_e32 v149, 0xffff0000, v185
	v_lshlrev_b32_e32 v150, 16, v186
	v_and_b32_e32 v151, 0xffff0000, v186
	v_lshlrev_b32_e32 v152, 16, v187
	v_and_b32_e32 v153, 0xffff0000, v187
	v_pk_mul_f32 v[154:155], v[108:109], v[146:147]
	v_pk_mul_f32 v[156:157], v[110:111], v[148:149]
	v_pk_mul_f32 v[158:159], v[104:105], v[150:151]
	v_pk_mul_f32 v[160:161], v[106:107], v[152:153]
	v_add_u32_e32 v144, 0x40000, v143
	v_cvt_pk_bf16_f32 v184, v154, v155
	v_cvt_pk_bf16_f32 v185, v156, v157
	v_cvt_pk_bf16_f32 v186, v158, v159
	v_cvt_pk_bf16_f32 v187, v160, v161
	global_store_dwordx4 v144, v[184:187], s[72:73]
	s_waitcnt vmcnt(15)
	v_lshlrev_b32_e32 v146, 16, v188
	v_and_b32_e32 v147, 0xffff0000, v188
	v_lshlrev_b32_e32 v148, 16, v189
	v_and_b32_e32 v149, 0xffff0000, v189
	v_lshlrev_b32_e32 v150, 16, v190
	v_and_b32_e32 v151, 0xffff0000, v190
	v_lshlrev_b32_e32 v152, 16, v191
	v_and_b32_e32 v153, 0xffff0000, v191
	v_pk_mul_f32 v[154:155], v[76:77], v[146:147]
	v_pk_mul_f32 v[156:157], v[78:79], v[148:149]
	v_pk_mul_f32 v[158:159], v[72:73], v[150:151]
	v_pk_mul_f32 v[160:161], v[74:75], v[152:153]
	v_cvt_pk_bf16_f32 v188, v154, v155
	v_cvt_pk_bf16_f32 v189, v156, v157
	v_cvt_pk_bf16_f32 v190, v158, v159
	v_cvt_pk_bf16_f32 v191, v160, v161
	global_store_dwordx4 v144, v[188:191], s[72:73] offset:256
	s_waitcnt vmcnt(15)
	v_lshlrev_b32_e32 v146, 16, v192
	v_and_b32_e32 v147, 0xffff0000, v192
	v_lshlrev_b32_e32 v148, 16, v193
	v_and_b32_e32 v149, 0xffff0000, v193
	v_lshlrev_b32_e32 v150, 16, v194
	v_and_b32_e32 v151, 0xffff0000, v194
	v_lshlrev_b32_e32 v152, 16, v195
	v_and_b32_e32 v153, 0xffff0000, v195
	v_pk_mul_f32 v[154:155], v[100:101], v[146:147]
	v_pk_mul_f32 v[156:157], v[102:103], v[148:149]
	v_pk_mul_f32 v[158:159], v[96:97], v[150:151]
	v_pk_mul_f32 v[160:161], v[98:99], v[152:153]
	v_add_u32_e32 v145, 0x60000, v143
	v_cvt_pk_bf16_f32 v192, v154, v155
	v_cvt_pk_bf16_f32 v193, v156, v157
	v_cvt_pk_bf16_f32 v194, v158, v159
	v_cvt_pk_bf16_f32 v195, v160, v161
	global_store_dwordx4 v145, v[192:195], s[72:73]
	s_waitcnt vmcnt(15)
	v_lshlrev_b32_e32 v146, 16, v196
	v_and_b32_e32 v147, 0xffff0000, v196
	v_lshlrev_b32_e32 v148, 16, v197
	v_and_b32_e32 v149, 0xffff0000, v197
	v_lshlrev_b32_e32 v150, 16, v198
	v_and_b32_e32 v151, 0xffff0000, v198
	v_lshlrev_b32_e32 v152, 16, v199
	v_and_b32_e32 v153, 0xffff0000, v199
	v_pk_mul_f32 v[154:155], v[68:69], v[146:147]
	v_pk_mul_f32 v[156:157], v[70:71], v[148:149]
	v_pk_mul_f32 v[158:159], v[64:65], v[150:151]
	v_pk_mul_f32 v[160:161], v[66:67], v[152:153]
	v_cvt_pk_bf16_f32 v196, v154, v155
	v_cvt_pk_bf16_f32 v197, v156, v157
	v_cvt_pk_bf16_f32 v198, v158, v159
	v_cvt_pk_bf16_f32 v199, v160, v161
	global_store_dwordx4 v145, v[196:199], s[72:73] offset:256
	s_waitcnt vmcnt(15)
	v_lshlrev_b32_e32 v146, 16, v200
	v_and_b32_e32 v147, 0xffff0000, v200
	v_lshlrev_b32_e32 v148, 16, v201
	v_and_b32_e32 v149, 0xffff0000, v201
	v_lshlrev_b32_e32 v150, 16, v202
	v_and_b32_e32 v151, 0xffff0000, v202
	v_lshlrev_b32_e32 v152, 16, v203
	v_and_b32_e32 v153, 0xffff0000, v203
	v_pk_mul_f32 v[154:155], v[60:61], v[146:147]
	v_pk_mul_f32 v[156:157], v[62:63], v[148:149]
	v_pk_mul_f32 v[158:159], v[56:57], v[150:151]
	v_pk_mul_f32 v[160:161], v[58:59], v[152:153]
	v_add_u32_e32 v144, 0x100000, v143
	v_cvt_pk_bf16_f32 v200, v154, v155
	v_cvt_pk_bf16_f32 v201, v156, v157
	v_cvt_pk_bf16_f32 v202, v158, v159
	v_cvt_pk_bf16_f32 v203, v160, v161
	global_store_dwordx4 v144, v[200:203], s[72:73]
	s_waitcnt vmcnt(15)
	v_lshlrev_b32_e32 v146, 16, v204
	v_and_b32_e32 v147, 0xffff0000, v204
	v_lshlrev_b32_e32 v148, 16, v205
	v_and_b32_e32 v149, 0xffff0000, v205
	v_lshlrev_b32_e32 v150, 16, v206
	v_and_b32_e32 v151, 0xffff0000, v206
	v_lshlrev_b32_e32 v152, 16, v207
	v_and_b32_e32 v153, 0xffff0000, v207
	v_pk_mul_f32 v[154:155], v[28:29], v[146:147]
	v_pk_mul_f32 v[156:157], v[30:31], v[148:149]
	v_pk_mul_f32 v[158:159], v[24:25], v[150:151]
	v_pk_mul_f32 v[160:161], v[26:27], v[152:153]
	v_cvt_pk_bf16_f32 v204, v154, v155
	v_cvt_pk_bf16_f32 v205, v156, v157
	v_cvt_pk_bf16_f32 v206, v158, v159
	v_cvt_pk_bf16_f32 v207, v160, v161
	global_store_dwordx4 v144, v[204:207], s[72:73] offset:256
	s_waitcnt vmcnt(15)
	v_lshlrev_b32_e32 v146, 16, v208
	v_and_b32_e32 v147, 0xffff0000, v208
	v_lshlrev_b32_e32 v148, 16, v209
	v_and_b32_e32 v149, 0xffff0000, v209
	v_lshlrev_b32_e32 v150, 16, v210
	v_and_b32_e32 v151, 0xffff0000, v210
	v_lshlrev_b32_e32 v152, 16, v211
	v_and_b32_e32 v153, 0xffff0000, v211
	v_pk_mul_f32 v[154:155], v[52:53], v[146:147]
	v_pk_mul_f32 v[156:157], v[54:55], v[148:149]
	v_pk_mul_f32 v[158:159], v[48:49], v[150:151]
	v_pk_mul_f32 v[160:161], v[50:51], v[152:153]
	v_add_u32_e32 v145, 0x120000, v143
	v_cvt_pk_bf16_f32 v208, v154, v155
	v_cvt_pk_bf16_f32 v209, v156, v157
	v_cvt_pk_bf16_f32 v210, v158, v159
	v_cvt_pk_bf16_f32 v211, v160, v161
	global_store_dwordx4 v145, v[208:211], s[72:73]
	s_waitcnt vmcnt(15)
	v_lshlrev_b32_e32 v146, 16, v212
	v_and_b32_e32 v147, 0xffff0000, v212
	v_lshlrev_b32_e32 v148, 16, v213
	v_and_b32_e32 v149, 0xffff0000, v213
	v_lshlrev_b32_e32 v150, 16, v214
	v_and_b32_e32 v151, 0xffff0000, v214
	v_lshlrev_b32_e32 v152, 16, v215
	v_and_b32_e32 v153, 0xffff0000, v215
	v_pk_mul_f32 v[154:155], v[20:21], v[146:147]
	v_pk_mul_f32 v[156:157], v[22:23], v[148:149]
	v_pk_mul_f32 v[158:159], v[16:17], v[150:151]
	v_pk_mul_f32 v[160:161], v[18:19], v[152:153]
	v_cvt_pk_bf16_f32 v212, v154, v155
	v_cvt_pk_bf16_f32 v213, v156, v157
	v_cvt_pk_bf16_f32 v214, v158, v159
	v_cvt_pk_bf16_f32 v215, v160, v161
	global_store_dwordx4 v145, v[212:215], s[72:73] offset:256
	s_waitcnt vmcnt(15)
	v_lshlrev_b32_e32 v146, 16, v216
	v_and_b32_e32 v147, 0xffff0000, v216
	v_lshlrev_b32_e32 v148, 16, v217
	v_and_b32_e32 v149, 0xffff0000, v217
	v_lshlrev_b32_e32 v150, 16, v218
	v_and_b32_e32 v151, 0xffff0000, v218
	v_lshlrev_b32_e32 v152, 16, v219
	v_and_b32_e32 v153, 0xffff0000, v219
	v_pk_mul_f32 v[154:155], v[44:45], v[146:147]
	v_pk_mul_f32 v[156:157], v[46:47], v[148:149]
	v_pk_mul_f32 v[158:159], v[40:41], v[150:151]
	v_pk_mul_f32 v[160:161], v[42:43], v[152:153]
	v_add_u32_e32 v144, 0x140000, v143
	v_cvt_pk_bf16_f32 v216, v154, v155
	v_cvt_pk_bf16_f32 v217, v156, v157
	v_cvt_pk_bf16_f32 v218, v158, v159
	v_cvt_pk_bf16_f32 v219, v160, v161
	global_store_dwordx4 v144, v[216:219], s[72:73]
	s_waitcnt vmcnt(15)
	v_lshlrev_b32_e32 v146, 16, v220
	v_and_b32_e32 v147, 0xffff0000, v220
	v_lshlrev_b32_e32 v148, 16, v221
	v_and_b32_e32 v149, 0xffff0000, v221
	v_lshlrev_b32_e32 v150, 16, v222
	v_and_b32_e32 v151, 0xffff0000, v222
	v_lshlrev_b32_e32 v152, 16, v223
	v_and_b32_e32 v153, 0xffff0000, v223
	v_pk_mul_f32 v[154:155], v[12:13], v[146:147]
	v_pk_mul_f32 v[156:157], v[14:15], v[148:149]
	v_pk_mul_f32 v[158:159], v[8:9], v[150:151]
	v_pk_mul_f32 v[160:161], v[10:11], v[152:153]
	v_cvt_pk_bf16_f32 v220, v154, v155
	v_cvt_pk_bf16_f32 v221, v156, v157
	v_cvt_pk_bf16_f32 v222, v158, v159
	v_cvt_pk_bf16_f32 v223, v160, v161
	global_store_dwordx4 v144, v[220:223], s[72:73] offset:256
	s_waitcnt vmcnt(15)
	v_lshlrev_b32_e32 v146, 16, v224
	v_and_b32_e32 v147, 0xffff0000, v224
	v_lshlrev_b32_e32 v148, 16, v225
	v_and_b32_e32 v149, 0xffff0000, v225
	v_lshlrev_b32_e32 v150, 16, v226
	v_and_b32_e32 v151, 0xffff0000, v226
	v_lshlrev_b32_e32 v152, 16, v227
	v_and_b32_e32 v153, 0xffff0000, v227
	v_pk_mul_f32 v[154:155], v[36:37], v[146:147]
	v_pk_mul_f32 v[156:157], v[38:39], v[148:149]
	v_pk_mul_f32 v[158:159], v[32:33], v[150:151]
	v_pk_mul_f32 v[160:161], v[34:35], v[152:153]
	v_add_u32_e32 v145, 0x160000, v143
	v_cvt_pk_bf16_f32 v224, v154, v155
	v_cvt_pk_bf16_f32 v225, v156, v157
	v_cvt_pk_bf16_f32 v226, v158, v159
	v_cvt_pk_bf16_f32 v227, v160, v161
	global_store_dwordx4 v145, v[224:227], s[72:73]
	s_waitcnt vmcnt(15)
	v_lshlrev_b32_e32 v146, 16, v228
	v_and_b32_e32 v147, 0xffff0000, v228
	v_lshlrev_b32_e32 v148, 16, v229
	v_and_b32_e32 v149, 0xffff0000, v229
	v_lshlrev_b32_e32 v150, 16, v230
	v_and_b32_e32 v151, 0xffff0000, v230
	v_lshlrev_b32_e32 v152, 16, v231
	v_and_b32_e32 v153, 0xffff0000, v231
	v_pk_mul_f32 v[154:155], v[4:5], v[146:147]
	v_pk_mul_f32 v[156:157], v[6:7], v[148:149]
	v_pk_mul_f32 v[158:159], v[0:1], v[150:151]
	v_pk_mul_f32 v[160:161], v[2:3], v[152:153]
	v_cvt_pk_bf16_f32 v228, v154, v155
	v_cvt_pk_bf16_f32 v229, v156, v157
	v_cvt_pk_bf16_f32 v230, v158, v159
	v_cvt_pk_bf16_f32 v231, v160, v161
	global_store_dwordx4 v145, v[228:231], s[72:73] offset:256
